# combo12 + UP epilogue VALU trim: store addresses as SGPR base + 32-bit offset (v_mad_u32_u24) instead of 64-bit mad/add chains; row-scale broadcasts via op_sel instead of v_mov pairs
# baseline (speedup 1.0000x reference)
.LBB0_120:
	v_lshl_or_b32 v184, s15, 7, v237
	v_cndmask_b32_e64 v2, 0, 1, s[4:5]
	v_mov_b32_e32 v213, v212
	v_mov_b32_e32 v211, v210
	v_mov_b32_e32 v209, v208
	v_mov_b32_e32 v199, v198
	v_lshlrev_b32_e32 v185, 1, v184
	v_cmp_ne_u32_e32 vcc, 0, v2
	v_pk_mul_f32 v[150:151], v[150:151], v[212:213] op_sel_hi:[1,0]
	v_pk_mul_f32 v[148:149], v[148:149], v[212:213] op_sel_hi:[1,0]
	v_pk_mul_f32 v[154:155], v[154:155], v[212:213] op_sel_hi:[1,0]
	v_pk_mul_f32 v[152:153], v[152:153], v[212:213] op_sel_hi:[1,0]
	v_pk_mul_f32 v[134:135], v[134:135], v[210:211] op_sel_hi:[1,0]
	v_pk_mul_f32 v[132:133], v[132:133], v[210:211] op_sel_hi:[1,0]
	v_pk_mul_f32 v[142:143], v[142:143], v[210:211] op_sel_hi:[1,0]
	v_pk_mul_f32 v[140:141], v[140:141], v[210:211] op_sel_hi:[1,0]
	v_pk_mul_f32 v[138:139], v[138:139], v[208:209] op_sel_hi:[1,0]
	v_pk_mul_f32 v[136:137], v[136:137], v[208:209] op_sel_hi:[1,0]
	v_pk_mul_f32 v[146:147], v[146:147], v[208:209] op_sel_hi:[1,0]
	v_pk_mul_f32 v[144:145], v[144:145], v[208:209] op_sel_hi:[1,0]
	v_pk_mul_f32 v[200:201], v[162:163], v[198:199] op_sel_hi:[1,0]
	v_pk_mul_f32 v[202:203], v[160:161], v[198:199] op_sel_hi:[1,0]
	v_pk_mul_f32 v[204:205], v[158:159], v[198:199] op_sel_hi:[1,0]
	v_pk_mul_f32 v[206:207], v[156:157], v[198:199] op_sel_hi:[1,0]
	s_movk_i32 s15, 0x4000
	s_movk_i32 s33, 0x1600
	s_cbranch_vccz .LBB0_140
	s_add_i32 s6, s9, -2
	v_add_u32_e32 v2, s6, v223
	v_med3_i32 v164, v2, 0, v229
	v_and_b32_e32 v164, 0x1fff, v164
	v_cmp_gt_u32_e64 s[0:1], 2, v164
	v_mov_b32_dpp v156, v202 row_shr:1 row_mask:0xf bank_mask:0xf bound_ctrl:1
	v_mov_b32_dpp v160, v206 row_shr:1 row_mask:0xf bank_mask:0xf bound_ctrl:1
	v_mov_b32_dpp v214, v136 row_shr:1 row_mask:0xf bank_mask:0xf bound_ctrl:1
	v_mov_b32_dpp v218, v144 row_shr:1 row_mask:0xf bank_mask:0xf bound_ctrl:1
	v_mov_b32_dpp v157, v203 row_shr:1 row_mask:0xf bank_mask:0xf bound_ctrl:1
	v_mov_b32_dpp v161, v207 row_shr:1 row_mask:0xf bank_mask:0xf bound_ctrl:1
	v_mov_b32_dpp v215, v137 row_shr:1 row_mask:0xf bank_mask:0xf bound_ctrl:1
	v_mov_b32_dpp v219, v145 row_shr:1 row_mask:0xf bank_mask:0xf bound_ctrl:1
	v_mov_b32_dpp v158, v200 row_shr:1 row_mask:0xf bank_mask:0xf bound_ctrl:1
	v_mov_b32_dpp v162, v204 row_shr:1 row_mask:0xf bank_mask:0xf bound_ctrl:1
	v_mov_b32_dpp v216, v138 row_shr:1 row_mask:0xf bank_mask:0xf bound_ctrl:1
	v_mov_b32_dpp v220, v146 row_shr:1 row_mask:0xf bank_mask:0xf bound_ctrl:1
	v_mov_b32_dpp v159, v201 row_shr:1 row_mask:0xf bank_mask:0xf bound_ctrl:1
	v_mov_b32_dpp v163, v205 row_shr:1 row_mask:0xf bank_mask:0xf bound_ctrl:1
	v_mov_b32_dpp v217, v139 row_shr:1 row_mask:0xf bank_mask:0xf bound_ctrl:1
	v_mov_b32_dpp v221, v147 row_shr:1 row_mask:0xf bank_mask:0xf bound_ctrl:1
	s_mov_b64 vcc, s[0:1]
	s_cbranch_vccz .LBB0_141
	v_cmp_eq_u32_e32 vcc, 0, v164
	s_and_saveexec_b64 s[4:5], s[0:1]
	v_mov_b32_e32 v221, 0
	v_mov_b32_e32 v220, 0
	v_mov_b32_e32 v219, 0
	v_mov_b32_e32 v218, 0
	v_mov_b32_e32 v217, 0
	v_mov_b32_e32 v216, 0
	v_mov_b32_e32 v215, 0
	v_mov_b32_e32 v214, 0
	s_or_b64 exec, exec, s[4:5]
	v_cndmask_b32_e64 v167, v159, 0, vcc
	v_cndmask_b32_e64 v166, v158, 0, vcc
	v_cndmask_b32_e64 v165, v157, 0, vcc
	v_cndmask_b32_e64 v164, v156, 0, vcc
	v_cndmask_b32_e64 v171, v163, 0, vcc
	v_cndmask_b32_e64 v170, v162, 0, vcc
	v_cndmask_b32_e64 v169, v161, 0, vcc
	v_cndmask_b32_e64 v168, v160, 0, vcc
	v_cmp_gt_i32_e32 vcc, s15, v2
	s_and_b64 s[4:5], s[38:39], vcc
	s_and_saveexec_b64 s[0:1], s[4:5]
	s_cbranch_execz .LBB0_126
.LBB0_125:
	s_waitcnt lgkmcnt(0)
	v_pk_fma_f32 v[218:219], v[56:57], v[218:219], v[64:65]
	v_pk_fma_f32 v[216:217], v[42:43], v[216:217], v[50:51]
	v_pk_fma_f32 v[214:215], v[40:41], v[214:215], v[48:49]
	v_pk_fma_f32 v[168:169], v[60:61], v[168:169], v[218:219]
	v_pk_fma_f32 v[166:167], v[46:47], v[166:167], v[216:217]
	v_pk_fma_f32 v[164:165], v[44:45], v[164:165], v[214:215]
	v_pk_fma_f32 v[220:221], v[58:59], v[220:221], v[66:67]
	v_pk_fma_f32 v[168:169], v[152:153], v[52:53], v[168:169]
	s_mov_b32 s4, 0xc0135761
	v_pk_fma_f32 v[166:167], v[150:151], v[38:39], v[166:167]
	v_pk_fma_f32 v[164:165], v[148:149], v[36:37], v[164:165]
	v_pk_fma_f32 v[170:171], v[62:63], v[170:171], v[220:221]
	v_pk_mul_f32 v[220:221], v[168:169], v[168:169]
	v_mov_b64_e32 v[246:247], s[4:5]
	s_mov_b32 s4, 0x3dd2d3e2
	v_pk_mul_f32 v[214:215], v[166:167], v[166:167]
	v_pk_mul_f32 v[216:217], v[164:165], v[164:165]
	v_pk_fma_f32 v[220:221], v[220:221], s[4:5], v[246:247] op_sel_hi:[1,0,0] neg_lo:[1,0,0] neg_hi:[1,0,0]
	v_pk_fma_f32 v[216:217], v[216:217], s[4:5], v[246:247] op_sel_hi:[1,0,0] neg_lo:[1,0,0] neg_hi:[1,0,0]
	v_pk_fma_f32 v[214:215], v[214:215], s[4:5], v[246:247] op_sel_hi:[1,0,0] neg_lo:[1,0,0] neg_hi:[1,0,0]
	v_pk_mul_f32 v[220:221], v[168:169], v[220:221]
	v_pk_mul_f32 v[214:215], v[166:167], v[214:215]
	v_pk_mul_f32 v[216:217], v[164:165], v[216:217]
	v_pk_fma_f32 v[170:171], v[154:155], v[54:55], v[170:171]
	v_exp_f32_e32 v220, v220
	v_exp_f32_e32 v221, v221
	v_exp_f32_e32 v216, v216
	v_exp_f32_e32 v214, v214
	v_exp_f32_e32 v215, v215
	v_exp_f32_e32 v217, v217
	v_pk_mul_f32 v[218:219], v[170:171], v[170:171]
	v_pk_add_f32 v[220:221], v[220:221], 1.0 op_sel_hi:[1,0]
	v_pk_fma_f32 v[218:219], v[218:219], s[4:5], v[246:247] op_sel_hi:[1,0,0] neg_lo:[1,0,0] neg_hi:[1,0,0]
	v_pk_add_f32 v[214:215], v[214:215], 1.0 op_sel_hi:[1,0]
	v_pk_mul_f32 v[218:219], v[170:171], v[218:219]
	v_pk_add_f32 v[216:217], v[216:217], 1.0 op_sel_hi:[1,0]
	v_exp_f32_e32 v218, v218
	v_exp_f32_e32 v219, v219
	v_rcp_f32_e32 v220, v220
	v_rcp_f32_e32 v221, v221
	v_rcp_f32_e32 v216, v216
	v_rcp_f32_e32 v214, v214
	v_rcp_f32_e32 v215, v215
	v_rcp_f32_e32 v217, v217
	v_pk_add_f32 v[218:219], v[218:219], 1.0 op_sel_hi:[1,0]
	v_pk_mul_f32 v[242:243], v[126:127], v[212:213] op_sel_hi:[1,0]
	v_pk_mul_f32 v[244:245], v[124:125], v[212:213]
	v_pk_mul_f32 v[248:249], v[128:129], v[212:213]
	v_rcp_f32_e32 v218, v218
	v_rcp_f32_e32 v219, v219
	v_pk_mul_f32 v[168:169], v[168:169], v[220:221]
	v_pk_mul_f32 v[166:167], v[166:167], v[214:215]
	v_pk_mul_f32 v[164:165], v[164:165], v[216:217]
	v_pk_mul_f32 v[168:169], v[248:249], v[168:169]
	v_pk_mul_f32 v[166:167], v[242:243], v[166:167]
	v_pk_mul_f32 v[164:165], v[244:245], v[164:165]
	v_pk_mul_f32 v[240:241], v[130:131], v[212:213] op_sel_hi:[1,0]
	v_cvt_pk_bf16_f32 v164, v164, v165
	v_cvt_pk_bf16_f32 v165, v166, v167
	v_cvt_pk_bf16_f32 v166, v168, v169
	v_mad_u32_u24 v168, v2, s33, v185
	v_pk_mul_f32 v[170:171], v[170:171], v[218:219]
	v_pk_mul_f32 v[170:171], v[240:241], v[170:171]
	s_nop 0
	v_cvt_pk_bf16_f32 v167, v170, v171
	global_store_dwordx4 v168, v[164:167], s[96:97]

.LBB0_130:
	s_waitcnt lgkmcnt(0)
	v_pk_fma_f32 v[160:161], v[56:57], v[160:161], v[64:65]
	v_pk_fma_f32 v[158:159], v[42:43], v[158:159], v[50:51]
	v_pk_fma_f32 v[156:157], v[40:41], v[156:157], v[48:49]
	v_pk_fma_f32 v[160:161], v[60:61], v[168:169], v[160:161]
	v_pk_fma_f32 v[158:159], v[46:47], v[166:167], v[158:159]
	v_pk_fma_f32 v[156:157], v[44:45], v[164:165], v[156:157]
	v_pk_fma_f32 v[162:163], v[58:59], v[162:163], v[66:67]
	v_pk_fma_f32 v[160:161], v[140:141], v[52:53], v[160:161]
	s_mov_b32 s4, 0xc0135761
	v_pk_fma_f32 v[158:159], v[134:135], v[38:39], v[158:159]
	v_pk_fma_f32 v[156:157], v[132:133], v[36:37], v[156:157]
	v_pk_fma_f32 v[162:163], v[62:63], v[170:171], v[162:163]
	v_pk_mul_f32 v[170:171], v[160:161], v[160:161]
	v_mov_b64_e32 v[240:241], s[4:5]
	s_mov_b32 s4, 0x3dd2d3e2
	v_pk_mul_f32 v[164:165], v[158:159], v[158:159]
	v_pk_mul_f32 v[166:167], v[156:157], v[156:157]
	v_pk_fma_f32 v[170:171], v[170:171], s[4:5], v[240:241] op_sel_hi:[1,0,0] neg_lo:[1,0,0] neg_hi:[1,0,0]
	v_pk_fma_f32 v[166:167], v[166:167], s[4:5], v[240:241] op_sel_hi:[1,0,0] neg_lo:[1,0,0] neg_hi:[1,0,0]
	v_pk_fma_f32 v[164:165], v[164:165], s[4:5], v[240:241] op_sel_hi:[1,0,0] neg_lo:[1,0,0] neg_hi:[1,0,0]
	v_pk_mul_f32 v[170:171], v[160:161], v[170:171]
	v_pk_mul_f32 v[164:165], v[158:159], v[164:165]
	v_pk_mul_f32 v[166:167], v[156:157], v[166:167]
	v_pk_fma_f32 v[162:163], v[142:143], v[54:55], v[162:163]
	v_exp_f32_e32 v170, v170
	v_exp_f32_e32 v171, v171
	v_exp_f32_e32 v166, v166
	v_exp_f32_e32 v167, v167
	v_exp_f32_e32 v164, v164
	v_exp_f32_e32 v165, v165
	v_pk_mul_f32 v[168:169], v[162:163], v[162:163]
	v_pk_add_f32 v[170:171], v[170:171], 1.0 op_sel_hi:[1,0]
	v_pk_fma_f32 v[168:169], v[168:169], s[4:5], v[240:241] op_sel_hi:[1,0,0] neg_lo:[1,0,0] neg_hi:[1,0,0]
	v_pk_add_f32 v[164:165], v[164:165], 1.0 op_sel_hi:[1,0]
	v_pk_mul_f32 v[168:169], v[162:163], v[168:169]
	v_pk_add_f32 v[166:167], v[166:167], 1.0 op_sel_hi:[1,0]
	v_exp_f32_e32 v168, v168
	v_exp_f32_e32 v169, v169
	v_rcp_f32_e32 v170, v170
	v_rcp_f32_e32 v171, v171
	v_rcp_f32_e32 v166, v166
	v_rcp_f32_e32 v167, v167
	v_rcp_f32_e32 v164, v164
	v_rcp_f32_e32 v165, v165
	v_pk_add_f32 v[168:169], v[168:169], 1.0 op_sel_hi:[1,0]
	v_pk_mul_f32 v[216:217], v[118:119], v[210:211] op_sel_hi:[1,0]
	v_pk_mul_f32 v[218:219], v[116:117], v[210:211]
	v_pk_mul_f32 v[220:221], v[120:121], v[210:211]
	v_rcp_f32_e32 v168, v168
	v_rcp_f32_e32 v169, v169
	v_pk_mul_f32 v[160:161], v[160:161], v[170:171]
	v_pk_mul_f32 v[158:159], v[158:159], v[164:165]
	v_pk_mul_f32 v[156:157], v[156:157], v[166:167]
	v_pk_mul_f32 v[160:161], v[220:221], v[160:161]
	v_pk_mul_f32 v[158:159], v[216:217], v[158:159]
	v_pk_mul_f32 v[156:157], v[218:219], v[156:157]
	v_pk_mul_f32 v[214:215], v[122:123], v[210:211] op_sel_hi:[1,0]
	v_cvt_pk_bf16_f32 v156, v156, v157
	v_cvt_pk_bf16_f32 v157, v158, v159
	v_cvt_pk_bf16_f32 v158, v160, v161
	v_mad_u32_u24 v160, v2, s33, v185
	v_pk_mul_f32 v[162:163], v[162:163], v[168:169]
	v_pk_mul_f32 v[162:163], v[214:215], v[162:163]
	s_nop 0
	v_cvt_pk_bf16_f32 v159, v162, v163
	global_store_dwordx4 v160, v[156:159], s[96:97]

.LBB0_135:
	s_waitcnt lgkmcnt(0)
	v_pk_fma_f32 v[168:169], v[56:57], v[168:169], v[64:65]
	v_pk_fma_f32 v[166:167], v[42:43], v[166:167], v[50:51]
	v_pk_fma_f32 v[164:165], v[40:41], v[164:165], v[48:49]
	v_pk_fma_f32 v[160:161], v[60:61], v[160:161], v[168:169]
	v_pk_fma_f32 v[158:159], v[46:47], v[158:159], v[166:167]
	v_pk_fma_f32 v[156:157], v[44:45], v[156:157], v[164:165]
	v_pk_fma_f32 v[170:171], v[58:59], v[170:171], v[66:67]
	v_pk_fma_f32 v[160:161], v[144:145], v[52:53], v[160:161]
	s_mov_b32 s4, 0xc0135761
	v_pk_fma_f32 v[158:159], v[138:139], v[38:39], v[158:159]
	v_pk_fma_f32 v[156:157], v[136:137], v[36:37], v[156:157]
	v_pk_fma_f32 v[162:163], v[62:63], v[162:163], v[170:171]
	v_pk_mul_f32 v[170:171], v[160:161], v[160:161]
	v_mov_b64_e32 v[220:221], s[4:5]
	s_mov_b32 s4, 0x3dd2d3e2
	v_pk_mul_f32 v[164:165], v[158:159], v[158:159]
	v_pk_mul_f32 v[166:167], v[156:157], v[156:157]
	v_pk_fma_f32 v[170:171], v[170:171], s[4:5], v[220:221] op_sel_hi:[1,0,0] neg_lo:[1,0,0] neg_hi:[1,0,0]
	v_pk_fma_f32 v[166:167], v[166:167], s[4:5], v[220:221] op_sel_hi:[1,0,0] neg_lo:[1,0,0] neg_hi:[1,0,0]
	v_pk_fma_f32 v[164:165], v[164:165], s[4:5], v[220:221] op_sel_hi:[1,0,0] neg_lo:[1,0,0] neg_hi:[1,0,0]
	v_pk_mul_f32 v[170:171], v[160:161], v[170:171]
	v_pk_mul_f32 v[164:165], v[158:159], v[164:165]
	v_pk_mul_f32 v[166:167], v[156:157], v[166:167]
	v_pk_fma_f32 v[162:163], v[146:147], v[54:55], v[162:163]
	v_exp_f32_e32 v170, v170
	v_exp_f32_e32 v171, v171
	v_exp_f32_e32 v166, v166
	v_exp_f32_e32 v164, v164
	v_exp_f32_e32 v165, v165
	v_exp_f32_e32 v167, v167
	v_pk_mul_f32 v[168:169], v[162:163], v[162:163]
	v_pk_add_f32 v[170:171], v[170:171], 1.0 op_sel_hi:[1,0]
	v_pk_fma_f32 v[168:169], v[168:169], s[4:5], v[220:221] op_sel_hi:[1,0,0] neg_lo:[1,0,0] neg_hi:[1,0,0]
	v_pk_add_f32 v[164:165], v[164:165], 1.0 op_sel_hi:[1,0]
	v_pk_mul_f32 v[168:169], v[162:163], v[168:169]
	v_pk_add_f32 v[166:167], v[166:167], 1.0 op_sel_hi:[1,0]
	v_exp_f32_e32 v168, v168
	v_exp_f32_e32 v169, v169
	v_rcp_f32_e32 v170, v170
	v_rcp_f32_e32 v171, v171
	v_rcp_f32_e32 v166, v166
	v_rcp_f32_e32 v164, v164
	v_rcp_f32_e32 v165, v165
	v_rcp_f32_e32 v167, v167
	v_pk_add_f32 v[168:169], v[168:169], 1.0 op_sel_hi:[1,0]
	v_pk_mul_f32 v[216:217], v[114:115], v[208:209] op_sel_hi:[1,0]
	v_pk_mul_f32 v[218:219], v[112:113], v[208:209]
	v_pk_mul_f32 v[240:241], v[108:109], v[208:209]
	v_rcp_f32_e32 v168, v168
	v_rcp_f32_e32 v169, v169
	v_pk_mul_f32 v[160:161], v[160:161], v[170:171]
	v_pk_mul_f32 v[158:159], v[158:159], v[164:165]
	v_pk_mul_f32 v[156:157], v[156:157], v[166:167]
	v_pk_mul_f32 v[160:161], v[240:241], v[160:161]
	v_pk_mul_f32 v[158:159], v[216:217], v[158:159]
	v_pk_mul_f32 v[156:157], v[218:219], v[156:157]
	v_pk_mul_f32 v[214:215], v[110:111], v[208:209] op_sel_hi:[1,0]
	v_cvt_pk_bf16_f32 v156, v156, v157
	v_cvt_pk_bf16_f32 v157, v158, v159
	v_cvt_pk_bf16_f32 v158, v160, v161
	v_mad_u32_u24 v160, v2, s33, v185
	v_pk_mul_f32 v[162:163], v[162:163], v[168:169]
	v_pk_mul_f32 v[162:163], v[214:215], v[162:163]
	s_nop 0
	v_cvt_pk_bf16_f32 v159, v162, v163
	global_store_dwordx4 v160, v[156:159], s[96:97]

.LBB0_145:
	v_cmp_gt_i32_e32 vcc, s15, v2
	s_mov_b64 s[0:1], 0
	s_mov_b64 s[4:5], 0
	s_and_saveexec_b64 s[6:7], vcc
	s_cbranch_execz .LBB0_147
	s_waitcnt lgkmcnt(0)
	v_pk_fma_f32 v[216:217], v[58:59], v[216:217], v[66:67]
	v_pk_fma_f32 v[214:215], v[56:57], v[214:215], v[64:65]
	v_pk_fma_f32 v[170:171], v[42:43], v[170:171], v[50:51]
	v_pk_fma_f32 v[168:169], v[40:41], v[168:169], v[48:49]
	v_pk_fma_f32 v[166:167], v[62:63], v[166:167], v[216:217]
	v_pk_fma_f32 v[164:165], v[60:61], v[164:165], v[214:215]
	v_pk_fma_f32 v[158:159], v[46:47], v[158:159], v[170:171]
	v_pk_fma_f32 v[156:157], v[44:45], v[156:157], v[168:169]
	v_pk_fma_f32 v[166:167], v[204:205], v[54:55], v[166:167]
	v_pk_fma_f32 v[164:165], v[206:207], v[52:53], v[164:165]
	s_mov_b32 s76, 0xc0135761
	v_pk_fma_f32 v[158:159], v[200:201], v[38:39], v[158:159]
	v_pk_fma_f32 v[156:157], v[202:203], v[36:37], v[156:157]
	v_pk_mul_f32 v[214:215], v[166:167], v[166:167]
	v_pk_mul_f32 v[216:217], v[164:165], v[164:165]
	v_mov_b64_e32 v[220:221], s[76:77]
	s_mov_b32 s76, 0x3dd2d3e2
	v_pk_mul_f32 v[168:169], v[158:159], v[158:159]
	v_pk_mul_f32 v[170:171], v[156:157], v[156:157]
	v_pk_fma_f32 v[216:217], v[216:217], s[76:77], v[220:221] op_sel_hi:[1,0,0] neg_lo:[1,0,0] neg_hi:[1,0,0]
	v_pk_fma_f32 v[214:215], v[214:215], s[76:77], v[220:221] op_sel_hi:[1,0,0] neg_lo:[1,0,0] neg_hi:[1,0,0]
	v_pk_fma_f32 v[170:171], v[170:171], s[76:77], v[220:221] op_sel_hi:[1,0,0] neg_lo:[1,0,0] neg_hi:[1,0,0]
	v_pk_fma_f32 v[168:169], v[168:169], s[76:77], v[220:221] op_sel_hi:[1,0,0] neg_lo:[1,0,0] neg_hi:[1,0,0]
	v_pk_mul_f32 v[214:215], v[166:167], v[214:215]
	v_pk_mul_f32 v[216:217], v[164:165], v[216:217]
	v_pk_mul_f32 v[168:169], v[158:159], v[168:169]
	v_pk_mul_f32 v[170:171], v[156:157], v[170:171]
	v_exp_f32_e32 v216, v216
	v_exp_f32_e32 v214, v214
	v_exp_f32_e32 v215, v215
	v_exp_f32_e32 v217, v217
	v_exp_f32_e32 v170, v170
	v_exp_f32_e32 v168, v168
	v_exp_f32_e32 v169, v169
	v_exp_f32_e32 v171, v171
	v_pk_add_f32 v[214:215], v[214:215], 1.0 op_sel_hi:[1,0]
	v_pk_add_f32 v[216:217], v[216:217], 1.0 op_sel_hi:[1,0]
	v_pk_add_f32 v[168:169], v[168:169], 1.0 op_sel_hi:[1,0]
	v_pk_add_f32 v[170:171], v[170:171], 1.0 op_sel_hi:[1,0]
	v_rcp_f32_e32 v216, v216
	v_rcp_f32_e32 v217, v217
	v_rcp_f32_e32 v214, v214
	v_rcp_f32_e32 v215, v215
	v_rcp_f32_e32 v170, v170
	v_rcp_f32_e32 v168, v168
	v_rcp_f32_e32 v169, v169
	v_rcp_f32_e32 v171, v171
	s_mov_b64 s[4:5], exec
	v_pk_mul_f32 v[162:163], v[106:107], v[198:199] op_sel_hi:[1,0]
	v_pk_mul_f32 v[218:219], v[104:105], v[198:199]
	v_pk_mul_f32 v[160:161], v[102:103], v[198:199] op_sel_hi:[1,0]
	v_pk_mul_f32 v[240:241], v[100:101], v[198:199]
	v_pk_mul_f32 v[166:167], v[166:167], v[214:215]
	v_pk_mul_f32 v[164:165], v[164:165], v[216:217]
	v_pk_mul_f32 v[158:159], v[158:159], v[168:169]
	v_pk_mul_f32 v[156:157], v[156:157], v[170:171]
	v_pk_mul_f32 v[166:167], v[160:161], v[166:167]
	v_pk_mul_f32 v[164:165], v[240:241], v[164:165]
	v_pk_mul_f32 v[158:159], v[162:163], v[158:159]
	v_pk_mul_f32 v[156:157], v[218:219], v[156:157]
	s_nop 0
	v_cvt_pk_bf16_f32 v160, v156, v157
	v_cvt_pk_bf16_f32 v161, v158, v159
	v_cvt_pk_bf16_f32 v162, v164, v165
	v_cvt_pk_bf16_f32 v163, v166, v167

.LBB0_148:
	v_mov_b32_dpp v156, v202 row_shr:1 row_mask:0xf bank_mask:0xf bound_ctrl:1
	v_mov_b32_dpp v160, v206 row_shr:1 row_mask:0xf bank_mask:0xf bound_ctrl:1
	v_mov_b32_dpp v164, v136 row_shr:1 row_mask:0xf bank_mask:0xf bound_ctrl:1
	v_mov_b32_dpp v168, v144 row_shr:1 row_mask:0xf bank_mask:0xf bound_ctrl:1
	v_mov_b32_dpp v157, v203 row_shr:1 row_mask:0xf bank_mask:0xf bound_ctrl:1
	v_mov_b32_dpp v161, v207 row_shr:1 row_mask:0xf bank_mask:0xf bound_ctrl:1
	v_mov_b32_dpp v165, v137 row_shr:1 row_mask:0xf bank_mask:0xf bound_ctrl:1
	v_mov_b32_dpp v169, v145 row_shr:1 row_mask:0xf bank_mask:0xf bound_ctrl:1
	v_mov_b32_dpp v158, v200 row_shr:1 row_mask:0xf bank_mask:0xf bound_ctrl:1
	v_mov_b32_dpp v162, v204 row_shr:1 row_mask:0xf bank_mask:0xf bound_ctrl:1
	v_mov_b32_dpp v166, v138 row_shr:1 row_mask:0xf bank_mask:0xf bound_ctrl:1
	v_mov_b32_dpp v170, v146 row_shr:1 row_mask:0xf bank_mask:0xf bound_ctrl:1
	v_mov_b32_dpp v159, v201 row_shr:1 row_mask:0xf bank_mask:0xf bound_ctrl:1
	v_mov_b32_dpp v163, v205 row_shr:1 row_mask:0xf bank_mask:0xf bound_ctrl:1
	v_mov_b32_dpp v167, v139 row_shr:1 row_mask:0xf bank_mask:0xf bound_ctrl:1
	v_mov_b32_dpp v171, v147 row_shr:1 row_mask:0xf bank_mask:0xf bound_ctrl:1
	s_and_saveexec_b64 s[0:1], s[38:39]
	s_cbranch_execz .LBB0_150
	v_mov_b32_e32 v214, v212
	v_mov_b32_e32 v215, v212
	v_pk_mul_f32 v[128:129], v[128:129], v[212:213]
	v_pk_mul_f32 v[212:213], v[124:125], v[212:213]
	s_waitcnt lgkmcnt(0)
	v_pk_fma_f32 v[124:125], v[58:59], v[170:171], v[66:67]
	v_pk_fma_f32 v[168:169], v[56:57], v[168:169], v[64:65]
	v_pk_fma_f32 v[124:125], v[62:63], v[162:163], v[124:125]
	v_pk_fma_f32 v[168:169], v[60:61], v[160:161], v[168:169]
	v_pk_fma_f32 v[170:171], v[154:155], v[54:55], v[124:125]
	v_pk_fma_f32 v[168:169], v[152:153], v[52:53], v[168:169]
	s_mov_b32 s4, 0xc0135761
	v_pk_mul_f32 v[130:131], v[130:131], v[214:215]
	v_pk_mul_f32 v[126:127], v[126:127], v[214:215]
	v_pk_mul_f32 v[214:215], v[170:171], v[170:171]
	v_pk_mul_f32 v[216:217], v[168:169], v[168:169]
	v_mov_b64_e32 v[124:125], s[4:5]
	s_mov_b32 s6, 0x3dd2d3e2
	v_pk_fma_f32 v[214:215], v[214:215], s[6:7], v[124:125] op_sel_hi:[1,0,0] neg_lo:[1,0,0] neg_hi:[1,0,0]
	v_pk_fma_f32 v[216:217], v[216:217], s[6:7], v[124:125] op_sel_hi:[1,0,0] neg_lo:[1,0,0] neg_hi:[1,0,0]
	v_pk_mul_f32 v[214:215], v[170:171], v[214:215]
	v_pk_mul_f32 v[216:217], v[168:169], v[216:217]
	v_exp_f32_e32 v214, v214
	v_exp_f32_e32 v216, v216
	v_exp_f32_e32 v217, v217
	v_exp_f32_e32 v215, v215
	v_pk_fma_f32 v[166:167], v[42:43], v[166:167], v[50:51]
	v_pk_fma_f32 v[164:165], v[40:41], v[164:165], v[48:49]
	v_pk_add_f32 v[216:217], v[216:217], 1.0 op_sel_hi:[1,0]
	v_pk_add_f32 v[214:215], v[214:215], 1.0 op_sel_hi:[1,0]
	v_rcp_f32_e32 v216, v216
	v_rcp_f32_e32 v217, v217
	v_rcp_f32_e32 v214, v214
	v_rcp_f32_e32 v215, v215
	v_pk_fma_f32 v[166:167], v[46:47], v[158:159], v[166:167]
	v_pk_fma_f32 v[164:165], v[44:45], v[156:157], v[164:165]
	v_pk_mul_f32 v[168:169], v[168:169], v[216:217]
	v_pk_mul_f32 v[170:171], v[170:171], v[214:215]
	v_pk_fma_f32 v[166:167], v[150:151], v[38:39], v[166:167]
	v_pk_fma_f32 v[164:165], v[148:149], v[36:37], v[164:165]
	v_pk_mul_f32 v[130:131], v[130:131], v[170:171]
	v_pk_mul_f32 v[128:129], v[128:129], v[168:169]
	v_pk_mul_f32 v[168:169], v[166:167], v[166:167]
	v_pk_mul_f32 v[170:171], v[164:165], v[164:165]
	v_pk_fma_f32 v[168:169], v[168:169], s[6:7], v[124:125] op_sel_hi:[1,0,0] neg_lo:[1,0,0] neg_hi:[1,0,0]
	v_pk_fma_f32 v[170:171], v[170:171], s[6:7], v[124:125] op_sel_hi:[1,0,0] neg_lo:[1,0,0] neg_hi:[1,0,0]
	v_pk_mul_f32 v[168:169], v[166:167], v[168:169]
	v_pk_mul_f32 v[170:171], v[164:165], v[170:171]
	v_exp_f32_e32 v168, v168
	v_exp_f32_e32 v170, v170
	v_exp_f32_e32 v171, v171
	v_exp_f32_e32 v169, v169
	v_add_u32_e32 v2, s9, v235
	v_pk_mul_f32 v[120:121], v[120:121], v[210:211]
	v_pk_add_f32 v[170:171], v[170:171], 1.0 op_sel_hi:[1,0]
	v_pk_add_f32 v[168:169], v[168:169], 1.0 op_sel_hi:[1,0]
	v_rcp_f32_e32 v170, v170
	v_rcp_f32_e32 v171, v171
	v_rcp_f32_e32 v168, v168
	v_rcp_f32_e32 v169, v169
	v_pk_mul_f32 v[116:117], v[116:117], v[210:211]
	v_pk_mul_f32 v[164:165], v[164:165], v[170:171]
	v_pk_mul_f32 v[166:167], v[166:167], v[168:169]
	s_nop 0
	v_pk_mul_f32 v[166:167], v[126:127], v[166:167]
	v_pk_mul_f32 v[126:127], v[212:213], v[164:165]
	s_nop 0
	v_cvt_pk_bf16_f32 v126, v126, v127
	v_cvt_pk_bf16_f32 v127, v166, v167
	v_cvt_pk_bf16_f32 v128, v128, v129
	v_cvt_pk_bf16_f32 v129, v130, v131
	v_mad_u32_u24 v164, v2, s33, v185
	global_store_dwordx4 v164, v[126:129], s[96:97]
	v_add_u32_e32 v2, s9, v236
	s_nop 0
	v_pk_mul_f32 v[122:123], v[122:123], v[210:211] op_sel_hi:[1,0]
	v_pk_mul_f32 v[118:119], v[118:119], v[210:211] op_sel_hi:[1,0]
	v_pk_fma_f32 v[126:127], v[58:59], v[162:163], v[66:67]
	v_pk_fma_f32 v[128:129], v[56:57], v[160:161], v[64:65]
	v_pk_fma_f32 v[126:127], v[154:155], v[62:63], v[126:127]
	v_pk_fma_f32 v[128:129], v[152:153], v[60:61], v[128:129]
	v_pk_fma_f32 v[126:127], v[142:143], v[54:55], v[126:127]
	v_pk_fma_f32 v[128:129], v[140:141], v[52:53], v[128:129]
	v_pk_mul_f32 v[160:161], v[126:127], v[126:127]
	v_pk_mul_f32 v[162:163], v[128:129], v[128:129]
	v_pk_fma_f32 v[160:161], v[160:161], s[6:7], v[124:125] op_sel_hi:[1,0,0] neg_lo:[1,0,0] neg_hi:[1,0,0]
	v_pk_fma_f32 v[162:163], v[162:163], s[6:7], v[124:125] op_sel_hi:[1,0,0] neg_lo:[1,0,0] neg_hi:[1,0,0]
	v_pk_mul_f32 v[160:161], v[126:127], v[160:161]
	v_pk_mul_f32 v[162:163], v[128:129], v[162:163]
	v_exp_f32_e32 v160, v160
	v_exp_f32_e32 v162, v162
	v_exp_f32_e32 v163, v163
	v_exp_f32_e32 v161, v161
	v_pk_add_f32 v[162:163], v[162:163], 1.0 op_sel_hi:[1,0]
	v_pk_add_f32 v[160:161], v[160:161], 1.0 op_sel_hi:[1,0]
	v_rcp_f32_e32 v162, v162
	v_rcp_f32_e32 v163, v163
	v_rcp_f32_e32 v160, v160
	v_rcp_f32_e32 v161, v161
	v_pk_mul_f32 v[128:129], v[128:129], v[162:163]
	s_nop 0
	v_pk_mul_f32 v[120:121], v[120:121], v[128:129]
	v_pk_mul_f32 v[126:127], v[126:127], v[160:161]
	v_pk_fma_f32 v[128:129], v[40:41], v[156:157], v[48:49]
	v_pk_mul_f32 v[122:123], v[122:123], v[126:127]
	v_pk_fma_f32 v[126:127], v[42:43], v[158:159], v[50:51]
	v_pk_fma_f32 v[128:129], v[148:149], v[44:45], v[128:129]
	v_pk_fma_f32 v[126:127], v[150:151], v[46:47], v[126:127]
	v_pk_fma_f32 v[128:129], v[132:133], v[36:37], v[128:129]
	v_pk_fma_f32 v[126:127], v[134:135], v[38:39], v[126:127]
	v_pk_mul_f32 v[158:159], v[128:129], v[128:129]
	v_pk_mul_f32 v[156:157], v[126:127], v[126:127]
	v_pk_fma_f32 v[158:159], v[158:159], s[6:7], v[124:125] op_sel_hi:[1,0,0] neg_lo:[1,0,0] neg_hi:[1,0,0]
	v_pk_fma_f32 v[124:125], v[156:157], s[6:7], v[124:125] op_sel_hi:[1,0,0] neg_lo:[1,0,0] neg_hi:[1,0,0]
	v_pk_mul_f32 v[156:157], v[128:129], v[158:159]
	v_pk_mul_f32 v[124:125], v[126:127], v[124:125]
	v_exp_f32_e32 v156, v156
	v_exp_f32_e32 v157, v157
	v_exp_f32_e32 v124, v124
	v_exp_f32_e32 v125, v125
	v_pk_add_f32 v[156:157], v[156:157], 1.0 op_sel_hi:[1,0]
	s_nop 0
	v_rcp_f32_e32 v156, v156
	v_pk_add_f32 v[124:125], v[124:125], 1.0 op_sel_hi:[1,0]
	v_rcp_f32_e32 v157, v157
	v_rcp_f32_e32 v124, v124
	v_rcp_f32_e32 v125, v125
	s_nop 0
	v_pk_mul_f32 v[124:125], v[126:127], v[124:125]
	v_pk_mul_f32 v[126:127], v[128:129], v[156:157]
	v_pk_mul_f32 v[118:119], v[118:119], v[124:125]
	v_pk_mul_f32 v[116:117], v[116:117], v[126:127]
	s_nop 0
	v_cvt_pk_bf16_f32 v116, v116, v117
	v_cvt_pk_bf16_f32 v117, v118, v119
	v_cvt_pk_bf16_f32 v118, v120, v121
	v_mad_u32_u24 v120, v2, s33, v185
	v_cvt_pk_bf16_f32 v119, v122, v123
	global_store_dwordx4 v120, v[116:119], s[96:97]
.LBB0_150:
	s_or_b64 exec, exec, s[0:1]
	s_nop 0
	v_pk_mul_f32 v[114:115], v[114:115], v[208:209] op_sel_hi:[1,0]
	v_pk_mul_f32 v[110:111], v[110:111], v[208:209] op_sel_hi:[1,0]
	v_pk_mul_f32 v[116:117], v[108:109], v[208:209]
	s_waitcnt lgkmcnt(0)
	v_pk_fma_f32 v[108:109], v[154:155], v[58:59], v[66:67]
	v_pk_fma_f32 v[118:119], v[152:153], v[56:57], v[64:65]
	v_pk_fma_f32 v[108:109], v[142:143], v[62:63], v[108:109]
	v_pk_fma_f32 v[118:119], v[140:141], v[60:61], v[118:119]
	v_pk_fma_f32 v[120:121], v[146:147], v[54:55], v[108:109]
	v_pk_fma_f32 v[118:119], v[144:145], v[52:53], v[118:119]
	s_mov_b32 s0, 0xc0135761
	v_pk_mul_f32 v[122:123], v[120:121], v[120:121]
	v_pk_mul_f32 v[124:125], v[118:119], v[118:119]
	v_mov_b64_e32 v[108:109], s[0:1]
	s_mov_b32 s4, 0x3dd2d3e2
	v_pk_fma_f32 v[122:123], v[122:123], s[4:5], v[108:109] op_sel_hi:[1,0,0] neg_lo:[1,0,0] neg_hi:[1,0,0]
	v_pk_fma_f32 v[124:125], v[124:125], s[4:5], v[108:109] op_sel_hi:[1,0,0] neg_lo:[1,0,0] neg_hi:[1,0,0]
	v_pk_mul_f32 v[122:123], v[120:121], v[122:123]
	v_pk_mul_f32 v[124:125], v[118:119], v[124:125]
	v_exp_f32_e32 v122, v122
	v_exp_f32_e32 v124, v124
	v_exp_f32_e32 v125, v125
	v_exp_f32_e32 v123, v123
	v_pk_mul_f32 v[112:113], v[112:113], v[208:209]
	v_add_u32_e32 v2, s9, v223
	v_pk_add_f32 v[124:125], v[124:125], 1.0 op_sel_hi:[1,0]
	v_pk_add_f32 v[122:123], v[122:123], 1.0 op_sel_hi:[1,0]
	v_rcp_f32_e32 v124, v124
	v_rcp_f32_e32 v125, v125
	v_rcp_f32_e32 v122, v122
	v_rcp_f32_e32 v123, v123
	v_pk_mul_f32 v[100:101], v[100:101], v[198:199]
	v_pk_mul_f32 v[118:119], v[118:119], v[124:125]
	v_pk_mul_f32 v[104:105], v[104:105], v[198:199]
	v_pk_mul_f32 v[120:121], v[120:121], v[122:123]
	v_pk_mul_f32 v[116:117], v[116:117], v[118:119]
	v_pk_mul_f32 v[120:121], v[110:111], v[120:121]
	v_pk_fma_f32 v[110:111], v[150:151], v[42:43], v[50:51]
	v_pk_fma_f32 v[118:119], v[148:149], v[40:41], v[48:49]
	v_pk_fma_f32 v[110:111], v[134:135], v[46:47], v[110:111]
	v_pk_fma_f32 v[118:119], v[132:133], v[44:45], v[118:119]
	v_pk_fma_f32 v[110:111], v[138:139], v[38:39], v[110:111]
	v_pk_fma_f32 v[118:119], v[136:137], v[36:37], v[118:119]
	v_pk_mul_f32 v[122:123], v[110:111], v[110:111]
	v_pk_mul_f32 v[124:125], v[118:119], v[118:119]
	v_pk_fma_f32 v[122:123], v[122:123], s[4:5], v[108:109] op_sel_hi:[1,0,0] neg_lo:[1,0,0] neg_hi:[1,0,0]
	v_pk_fma_f32 v[124:125], v[124:125], s[4:5], v[108:109] op_sel_hi:[1,0,0] neg_lo:[1,0,0] neg_hi:[1,0,0]
	v_pk_mul_f32 v[122:123], v[110:111], v[122:123]
	v_pk_mul_f32 v[124:125], v[118:119], v[124:125]
	v_exp_f32_e32 v122, v122
	v_exp_f32_e32 v124, v124
	v_exp_f32_e32 v125, v125
	v_exp_f32_e32 v123, v123
	v_pk_add_f32 v[124:125], v[124:125], 1.0 op_sel_hi:[1,0]
	v_pk_add_f32 v[122:123], v[122:123], 1.0 op_sel_hi:[1,0]
	v_rcp_f32_e32 v124, v124
	v_rcp_f32_e32 v125, v125
	v_rcp_f32_e32 v122, v122
	v_rcp_f32_e32 v123, v123
	v_pk_mul_f32 v[118:119], v[118:119], v[124:125]
	v_pk_mul_f32 v[110:111], v[110:111], v[122:123]
	s_nop 0
	v_pk_mul_f32 v[114:115], v[114:115], v[110:111]
	v_pk_mul_f32 v[110:111], v[112:113], v[118:119]
	s_nop 0
	v_cvt_pk_bf16_f32 v110, v110, v111
	v_cvt_pk_bf16_f32 v111, v114, v115
	v_mad_u32_u24 v114, v2, s33, v185
	v_cvt_pk_bf16_f32 v112, v116, v117
	v_cvt_pk_bf16_f32 v113, v120, v121
	global_store_dwordx4 v114, v[110:113], s[96:97]
	v_add_u32_e32 v2, s9, v233
	s_nop 0
	v_pk_mul_f32 v[106:107], v[106:107], v[198:199] op_sel_hi:[1,0]
	v_pk_mul_f32 v[102:103], v[102:103], v[198:199] op_sel_hi:[1,0]
	v_pk_fma_f32 v[110:111], v[142:143], v[58:59], v[66:67]
	v_pk_fma_f32 v[112:113], v[140:141], v[56:57], v[64:65]
	v_pk_fma_f32 v[110:111], v[146:147], v[62:63], v[110:111]
	v_pk_fma_f32 v[112:113], v[144:145], v[60:61], v[112:113]
	v_pk_fma_f32 v[110:111], v[204:205], v[54:55], v[110:111]
	v_pk_fma_f32 v[112:113], v[206:207], v[52:53], v[112:113]
	v_pk_mul_f32 v[114:115], v[110:111], v[110:111]
	v_pk_mul_f32 v[116:117], v[112:113], v[112:113]
	v_pk_fma_f32 v[114:115], v[114:115], s[4:5], v[108:109] op_sel_hi:[1,0,0] neg_lo:[1,0,0] neg_hi:[1,0,0]
	v_pk_fma_f32 v[116:117], v[116:117], s[4:5], v[108:109] op_sel_hi:[1,0,0] neg_lo:[1,0,0] neg_hi:[1,0,0]
	v_pk_mul_f32 v[114:115], v[110:111], v[114:115]
	v_pk_mul_f32 v[116:117], v[112:113], v[116:117]
	v_exp_f32_e32 v114, v114
	v_exp_f32_e32 v116, v116
	v_exp_f32_e32 v117, v117
	v_exp_f32_e32 v115, v115
	v_pk_add_f32 v[116:117], v[116:117], 1.0 op_sel_hi:[1,0]
	v_pk_add_f32 v[114:115], v[114:115], 1.0 op_sel_hi:[1,0]
	v_rcp_f32_e32 v116, v116
	v_rcp_f32_e32 v117, v117
	v_rcp_f32_e32 v114, v114
	v_rcp_f32_e32 v115, v115
	v_pk_mul_f32 v[112:113], v[112:113], v[116:117]
	s_nop 0
	v_pk_mul_f32 v[100:101], v[100:101], v[112:113]
	v_pk_mul_f32 v[110:111], v[110:111], v[114:115]
	v_pk_fma_f32 v[112:113], v[132:133], v[40:41], v[48:49]
	v_pk_mul_f32 v[102:103], v[102:103], v[110:111]
	v_pk_fma_f32 v[110:111], v[134:135], v[42:43], v[50:51]
	v_pk_fma_f32 v[112:113], v[136:137], v[44:45], v[112:113]
	v_pk_fma_f32 v[110:111], v[138:139], v[46:47], v[110:111]
	v_pk_fma_f32 v[112:113], v[202:203], v[36:37], v[112:113]
	v_pk_fma_f32 v[110:111], v[200:201], v[38:39], v[110:111]
	v_pk_mul_f32 v[116:117], v[112:113], v[112:113]
	v_pk_mul_f32 v[114:115], v[110:111], v[110:111]
	s_nop 0
	v_pk_fma_f32 v[114:115], v[114:115], s[4:5], v[108:109] op_sel_hi:[1,0,0] neg_lo:[1,0,0] neg_hi:[1,0,0]
	v_pk_fma_f32 v[108:109], v[116:117], s[4:5], v[108:109] op_sel_hi:[1,0,0] neg_lo:[1,0,0] neg_hi:[1,0,0]
	v_pk_mul_f32 v[114:115], v[110:111], v[114:115]
	v_pk_mul_f32 v[108:109], v[112:113], v[108:109]
	v_exp_f32_e32 v114, v114
	v_exp_f32_e32 v108, v108
	v_exp_f32_e32 v109, v109
	v_exp_f32_e32 v115, v115
	s_mov_b64 s[4:5], -1
	v_pk_add_f32 v[108:109], v[108:109], 1.0 op_sel_hi:[1,0]
	v_pk_add_f32 v[114:115], v[114:115], 1.0 op_sel_hi:[1,0]
	v_rcp_f32_e32 v108, v108
	v_rcp_f32_e32 v109, v109
	v_rcp_f32_e32 v114, v114
	v_rcp_f32_e32 v115, v115
	v_pk_mul_f32 v[108:109], v[112:113], v[108:109]
	s_nop 0
	v_pk_mul_f32 v[104:105], v[104:105], v[108:109]
	v_pk_mul_f32 v[110:111], v[110:111], v[114:115]
	v_cvt_pk_bf16_f32 v160, v104, v105
	s_nop 0
	v_pk_mul_f32 v[106:107], v[106:107], v[110:111]
	s_nop 0
	v_cvt_pk_bf16_f32 v161, v106, v107
	v_cvt_pk_bf16_f32 v162, v100, v101
	v_cvt_pk_bf16_f32 v163, v102, v103
.LBB0_151:
	s_and_saveexec_b64 s[0:1], s[4:5]
	s_cbranch_execz .LBB0_153
	v_mad_u32_u24 v100, v2, s33, v185
	global_store_dwordx4 v100, v[160:163], s[96:97]

.LBB0_160:
	s_waitcnt lgkmcnt(0)
	v_pk_fma_f32 v[120:121], v[56:57], v[120:121], v[64:65]
	v_pk_fma_f32 v[118:119], v[42:43], v[118:119], v[50:51]
	v_pk_fma_f32 v[116:117], v[40:41], v[116:117], v[48:49]
	v_pk_fma_f32 v[104:105], v[60:61], v[104:105], v[120:121]
	v_pk_fma_f32 v[102:103], v[46:47], v[102:103], v[118:119]
	v_pk_fma_f32 v[100:101], v[44:45], v[100:101], v[116:117]
	v_pk_fma_f32 v[122:123], v[58:59], v[122:123], v[66:67]
	v_pk_fma_f32 v[104:105], v[92:93], v[52:53], v[104:105]
	s_mov_b32 s4, 0xc0135761
	v_pk_fma_f32 v[102:103], v[98:99], v[38:39], v[102:103]
	v_pk_fma_f32 v[100:101], v[96:97], v[36:37], v[100:101]
	v_pk_fma_f32 v[106:107], v[62:63], v[106:107], v[122:123]
	v_pk_mul_f32 v[122:123], v[104:105], v[104:105]
	v_mov_b64_e32 v[130:131], s[4:5]
	s_mov_b32 s4, 0x3dd2d3e2
	v_pk_mul_f32 v[116:117], v[102:103], v[102:103]
	v_pk_mul_f32 v[118:119], v[100:101], v[100:101]
	v_pk_fma_f32 v[122:123], v[122:123], s[4:5], v[130:131] op_sel_hi:[1,0,0] neg_lo:[1,0,0] neg_hi:[1,0,0]
	v_pk_fma_f32 v[118:119], v[118:119], s[4:5], v[130:131] op_sel_hi:[1,0,0] neg_lo:[1,0,0] neg_hi:[1,0,0]
	v_pk_fma_f32 v[116:117], v[116:117], s[4:5], v[130:131] op_sel_hi:[1,0,0] neg_lo:[1,0,0] neg_hi:[1,0,0]
	v_pk_mul_f32 v[122:123], v[104:105], v[122:123]
	v_pk_mul_f32 v[116:117], v[102:103], v[116:117]
	v_pk_mul_f32 v[118:119], v[100:101], v[118:119]
	v_pk_fma_f32 v[106:107], v[94:95], v[54:55], v[106:107]
	v_exp_f32_e32 v122, v122
	v_exp_f32_e32 v123, v123
	v_exp_f32_e32 v118, v118
	v_exp_f32_e32 v116, v116
	v_exp_f32_e32 v117, v117
	v_exp_f32_e32 v119, v119
	v_pk_mul_f32 v[120:121], v[106:107], v[106:107]
	v_pk_add_f32 v[122:123], v[122:123], 1.0 op_sel_hi:[1,0]
	v_pk_fma_f32 v[120:121], v[120:121], s[4:5], v[130:131] op_sel_hi:[1,0,0] neg_lo:[1,0,0] neg_hi:[1,0,0]
	v_pk_add_f32 v[116:117], v[116:117], 1.0 op_sel_hi:[1,0]
	v_pk_mul_f32 v[120:121], v[106:107], v[120:121]
	v_pk_add_f32 v[118:119], v[118:119], 1.0 op_sel_hi:[1,0]
	v_exp_f32_e32 v120, v120
	v_exp_f32_e32 v121, v121
	v_rcp_f32_e32 v122, v122
	v_rcp_f32_e32 v123, v123
	v_rcp_f32_e32 v118, v118
	v_rcp_f32_e32 v116, v116
	v_rcp_f32_e32 v117, v117
	v_rcp_f32_e32 v119, v119
	v_pk_add_f32 v[120:121], v[120:121], 1.0 op_sel_hi:[1,0]
	v_pk_mul_f32 v[126:127], v[30:31], v[192:193] op_sel_hi:[1,0]
	v_pk_mul_f32 v[128:129], v[28:29], v[192:193]
	v_pk_mul_f32 v[132:133], v[32:33], v[192:193]
	v_rcp_f32_e32 v120, v120
	v_rcp_f32_e32 v121, v121
	v_pk_mul_f32 v[104:105], v[104:105], v[122:123]
	v_pk_mul_f32 v[102:103], v[102:103], v[116:117]
	v_pk_mul_f32 v[100:101], v[100:101], v[118:119]
	v_pk_mul_f32 v[104:105], v[132:133], v[104:105]
	v_pk_mul_f32 v[102:103], v[126:127], v[102:103]
	v_pk_mul_f32 v[100:101], v[128:129], v[100:101]
	v_pk_mul_f32 v[124:125], v[34:35], v[192:193] op_sel_hi:[1,0]
	v_cvt_pk_bf16_f32 v100, v100, v101
	v_cvt_pk_bf16_f32 v101, v102, v103
	v_cvt_pk_bf16_f32 v102, v104, v105
	v_mad_u32_u24 v104, v2, s33, v185
	v_pk_mul_f32 v[106:107], v[106:107], v[120:121]
	v_pk_mul_f32 v[106:107], v[124:125], v[106:107]
	s_nop 0
	v_cvt_pk_bf16_f32 v103, v106, v107
	global_store_dwordx4 v104, v[100:103], s[96:97]

.LBB0_165:
	s_waitcnt lgkmcnt(0)
	v_pk_fma_f32 v[72:73], v[56:57], v[72:73], v[64:65]
	v_pk_fma_f32 v[70:71], v[42:43], v[70:71], v[50:51]
	v_pk_fma_f32 v[68:69], v[40:41], v[68:69], v[48:49]
	v_pk_fma_f32 v[72:73], v[60:61], v[104:105], v[72:73]
	v_pk_fma_f32 v[70:71], v[46:47], v[102:103], v[70:71]
	v_pk_fma_f32 v[68:69], v[44:45], v[100:101], v[68:69]
	v_pk_fma_f32 v[74:75], v[58:59], v[74:75], v[66:67]
	v_pk_fma_f32 v[72:73], v[84:85], v[52:53], v[72:73]
	s_mov_b32 s4, 0xc0135761
	v_pk_fma_f32 v[70:71], v[90:91], v[38:39], v[70:71]
	v_pk_fma_f32 v[68:69], v[88:89], v[36:37], v[68:69]
	v_pk_fma_f32 v[74:75], v[62:63], v[106:107], v[74:75]
	v_pk_mul_f32 v[106:107], v[72:73], v[72:73]
	v_mov_b64_e32 v[124:125], s[4:5]
	s_mov_b32 s4, 0x3dd2d3e2
	v_pk_mul_f32 v[100:101], v[70:71], v[70:71]
	v_pk_mul_f32 v[102:103], v[68:69], v[68:69]
	v_pk_fma_f32 v[106:107], v[106:107], s[4:5], v[124:125] op_sel_hi:[1,0,0] neg_lo:[1,0,0] neg_hi:[1,0,0]
	v_pk_fma_f32 v[102:103], v[102:103], s[4:5], v[124:125] op_sel_hi:[1,0,0] neg_lo:[1,0,0] neg_hi:[1,0,0]
	v_pk_fma_f32 v[100:101], v[100:101], s[4:5], v[124:125] op_sel_hi:[1,0,0] neg_lo:[1,0,0] neg_hi:[1,0,0]
	v_pk_mul_f32 v[106:107], v[72:73], v[106:107]
	v_pk_mul_f32 v[100:101], v[70:71], v[100:101]
	v_pk_mul_f32 v[102:103], v[68:69], v[102:103]
	v_pk_fma_f32 v[74:75], v[86:87], v[54:55], v[74:75]
	v_exp_f32_e32 v106, v106
	v_exp_f32_e32 v107, v107
	v_exp_f32_e32 v102, v102
	v_exp_f32_e32 v103, v103
	v_exp_f32_e32 v100, v100
	v_exp_f32_e32 v101, v101
	v_pk_mul_f32 v[104:105], v[74:75], v[74:75]
	v_pk_add_f32 v[106:107], v[106:107], 1.0 op_sel_hi:[1,0]
	v_pk_fma_f32 v[104:105], v[104:105], s[4:5], v[124:125] op_sel_hi:[1,0,0] neg_lo:[1,0,0] neg_hi:[1,0,0]
	v_pk_add_f32 v[100:101], v[100:101], 1.0 op_sel_hi:[1,0]
	v_pk_mul_f32 v[104:105], v[74:75], v[104:105]
	v_pk_add_f32 v[102:103], v[102:103], 1.0 op_sel_hi:[1,0]
	v_exp_f32_e32 v104, v104
	v_exp_f32_e32 v105, v105
	v_rcp_f32_e32 v106, v106
	v_rcp_f32_e32 v107, v107
	v_rcp_f32_e32 v102, v102
	v_rcp_f32_e32 v103, v103
	v_rcp_f32_e32 v100, v100
	v_rcp_f32_e32 v101, v101
	v_pk_add_f32 v[104:105], v[104:105], 1.0 op_sel_hi:[1,0]
	v_pk_mul_f32 v[118:119], v[22:23], v[190:191] op_sel_hi:[1,0]
	v_pk_mul_f32 v[120:121], v[20:21], v[190:191]
	v_pk_mul_f32 v[122:123], v[24:25], v[190:191]
	v_rcp_f32_e32 v104, v104
	v_rcp_f32_e32 v105, v105
	v_pk_mul_f32 v[72:73], v[72:73], v[106:107]
	v_pk_mul_f32 v[70:71], v[70:71], v[100:101]
	v_pk_mul_f32 v[68:69], v[68:69], v[102:103]
	v_pk_mul_f32 v[72:73], v[122:123], v[72:73]
	v_pk_mul_f32 v[70:71], v[118:119], v[70:71]
	v_pk_mul_f32 v[68:69], v[120:121], v[68:69]
	v_pk_mul_f32 v[116:117], v[26:27], v[190:191] op_sel_hi:[1,0]
	v_cvt_pk_bf16_f32 v68, v68, v69
	v_cvt_pk_bf16_f32 v69, v70, v71
	v_cvt_pk_bf16_f32 v70, v72, v73
	v_mad_u32_u24 v72, v2, s33, v185
	v_pk_mul_f32 v[74:75], v[74:75], v[104:105]
	v_pk_mul_f32 v[74:75], v[116:117], v[74:75]
	s_nop 0
	v_cvt_pk_bf16_f32 v71, v74, v75
	global_store_dwordx4 v72, v[68:71], s[96:97]

.LBB0_170:
	s_waitcnt lgkmcnt(0)
	v_pk_fma_f32 v[104:105], v[56:57], v[104:105], v[64:65]
	v_pk_fma_f32 v[102:103], v[42:43], v[102:103], v[50:51]
	v_pk_fma_f32 v[100:101], v[40:41], v[100:101], v[48:49]
	v_pk_fma_f32 v[72:73], v[60:61], v[72:73], v[104:105]
	v_pk_fma_f32 v[70:71], v[46:47], v[70:71], v[102:103]
	v_pk_fma_f32 v[68:69], v[44:45], v[68:69], v[100:101]
	v_pk_fma_f32 v[106:107], v[58:59], v[106:107], v[66:67]
	v_pk_fma_f32 v[72:73], v[76:77], v[52:53], v[72:73]
	s_mov_b32 s4, 0xc0135761
	v_pk_fma_f32 v[70:71], v[82:83], v[38:39], v[70:71]
	v_pk_fma_f32 v[68:69], v[80:81], v[36:37], v[68:69]
	v_pk_fma_f32 v[74:75], v[62:63], v[74:75], v[106:107]
	v_pk_mul_f32 v[106:107], v[72:73], v[72:73]
	v_mov_b64_e32 v[122:123], s[4:5]
	s_mov_b32 s4, 0x3dd2d3e2
	v_pk_mul_f32 v[100:101], v[70:71], v[70:71]
	v_pk_mul_f32 v[102:103], v[68:69], v[68:69]
	v_pk_fma_f32 v[106:107], v[106:107], s[4:5], v[122:123] op_sel_hi:[1,0,0] neg_lo:[1,0,0] neg_hi:[1,0,0]
	v_pk_fma_f32 v[102:103], v[102:103], s[4:5], v[122:123] op_sel_hi:[1,0,0] neg_lo:[1,0,0] neg_hi:[1,0,0]
	v_pk_fma_f32 v[100:101], v[100:101], s[4:5], v[122:123] op_sel_hi:[1,0,0] neg_lo:[1,0,0] neg_hi:[1,0,0]
	v_pk_mul_f32 v[106:107], v[72:73], v[106:107]
	v_pk_mul_f32 v[100:101], v[70:71], v[100:101]
	v_pk_mul_f32 v[102:103], v[68:69], v[102:103]
	v_pk_fma_f32 v[74:75], v[78:79], v[54:55], v[74:75]
	v_exp_f32_e32 v106, v106
	v_exp_f32_e32 v107, v107
	v_exp_f32_e32 v102, v102
	v_exp_f32_e32 v100, v100
	v_exp_f32_e32 v101, v101
	v_exp_f32_e32 v103, v103
	v_pk_mul_f32 v[104:105], v[74:75], v[74:75]
	v_pk_add_f32 v[106:107], v[106:107], 1.0 op_sel_hi:[1,0]
	v_pk_fma_f32 v[104:105], v[104:105], s[4:5], v[122:123] op_sel_hi:[1,0,0] neg_lo:[1,0,0] neg_hi:[1,0,0]
	v_pk_add_f32 v[100:101], v[100:101], 1.0 op_sel_hi:[1,0]
	v_pk_mul_f32 v[104:105], v[74:75], v[104:105]
	v_pk_add_f32 v[102:103], v[102:103], 1.0 op_sel_hi:[1,0]
	v_exp_f32_e32 v104, v104
	v_exp_f32_e32 v105, v105
	v_rcp_f32_e32 v106, v106
	v_rcp_f32_e32 v107, v107
	v_rcp_f32_e32 v102, v102
	v_rcp_f32_e32 v100, v100
	v_rcp_f32_e32 v101, v101
	v_rcp_f32_e32 v103, v103
	v_pk_add_f32 v[104:105], v[104:105], 1.0 op_sel_hi:[1,0]
	v_pk_mul_f32 v[118:119], v[18:19], v[188:189] op_sel_hi:[1,0]
	v_pk_mul_f32 v[120:121], v[16:17], v[188:189]
	v_pk_mul_f32 v[124:125], v[12:13], v[188:189]
	v_rcp_f32_e32 v104, v104
	v_rcp_f32_e32 v105, v105
	v_pk_mul_f32 v[72:73], v[72:73], v[106:107]
	v_pk_mul_f32 v[70:71], v[70:71], v[100:101]
	v_pk_mul_f32 v[68:69], v[68:69], v[102:103]
	v_pk_mul_f32 v[72:73], v[124:125], v[72:73]
	v_pk_mul_f32 v[70:71], v[118:119], v[70:71]
	v_pk_mul_f32 v[68:69], v[120:121], v[68:69]
	v_pk_mul_f32 v[116:117], v[14:15], v[188:189] op_sel_hi:[1,0]
	v_cvt_pk_bf16_f32 v68, v68, v69
	v_cvt_pk_bf16_f32 v69, v70, v71
	v_cvt_pk_bf16_f32 v70, v72, v73
	v_mad_u32_u24 v72, v2, s33, v185
	v_pk_mul_f32 v[74:75], v[74:75], v[104:105]
	v_pk_mul_f32 v[74:75], v[116:117], v[74:75]
	s_nop 0
	v_cvt_pk_bf16_f32 v71, v74, v75
	global_store_dwordx4 v72, v[68:71], s[96:97]

.LBB0_177:
	v_mad_u32_u24 v4, v2, s33, v185
	global_store_dwordx4 v4, v[72:75], s[96:97]
	s_or_b64 exec, exec, s[0:1]
	s_and_b64 vcc, exec, s[40:41]
	s_mov_b64 s[0:1], -1
	s_cbranch_vccnz .LBB0_95
	s_branch .LBB0_189

.LBB0_182:
	v_cmp_gt_i32_e32 vcc, s15, v2
	s_mov_b64 s[0:1], 0
	s_mov_b64 s[4:5], 0
	s_and_saveexec_b64 s[6:7], vcc
	s_cbranch_execz .LBB0_184
	s_waitcnt lgkmcnt(0)
	v_pk_fma_f32 v[118:119], v[58:59], v[118:119], v[66:67]
	v_pk_fma_f32 v[116:117], v[56:57], v[116:117], v[64:65]
	v_pk_fma_f32 v[106:107], v[42:43], v[106:107], v[50:51]
	v_pk_fma_f32 v[104:105], v[40:41], v[104:105], v[48:49]
	v_pk_fma_f32 v[102:103], v[62:63], v[102:103], v[118:119]
	v_pk_fma_f32 v[100:101], v[60:61], v[100:101], v[116:117]
	v_pk_fma_f32 v[70:71], v[46:47], v[70:71], v[106:107]
	v_pk_fma_f32 v[68:69], v[44:45], v[68:69], v[104:105]
	v_pk_fma_f32 v[102:103], v[112:113], v[54:55], v[102:103]
	v_pk_fma_f32 v[100:101], v[114:115], v[52:53], v[100:101]
	s_mov_b32 s76, 0xc0135761
	v_pk_fma_f32 v[70:71], v[108:109], v[38:39], v[70:71]
	v_pk_fma_f32 v[68:69], v[110:111], v[36:37], v[68:69]
	v_pk_mul_f32 v[116:117], v[102:103], v[102:103]
	v_pk_mul_f32 v[118:119], v[100:101], v[100:101]
	v_mov_b64_e32 v[122:123], s[76:77]
	s_mov_b32 s76, 0x3dd2d3e2
	v_pk_mul_f32 v[104:105], v[70:71], v[70:71]
	v_pk_mul_f32 v[106:107], v[68:69], v[68:69]
	v_pk_fma_f32 v[118:119], v[118:119], s[76:77], v[122:123] op_sel_hi:[1,0,0] neg_lo:[1,0,0] neg_hi:[1,0,0]
	v_pk_fma_f32 v[116:117], v[116:117], s[76:77], v[122:123] op_sel_hi:[1,0,0] neg_lo:[1,0,0] neg_hi:[1,0,0]
	v_pk_fma_f32 v[106:107], v[106:107], s[76:77], v[122:123] op_sel_hi:[1,0,0] neg_lo:[1,0,0] neg_hi:[1,0,0]
	v_pk_fma_f32 v[104:105], v[104:105], s[76:77], v[122:123] op_sel_hi:[1,0,0] neg_lo:[1,0,0] neg_hi:[1,0,0]
	v_pk_mul_f32 v[116:117], v[102:103], v[116:117]
	v_pk_mul_f32 v[118:119], v[100:101], v[118:119]
	v_pk_mul_f32 v[104:105], v[70:71], v[104:105]
	v_pk_mul_f32 v[106:107], v[68:69], v[106:107]
	v_exp_f32_e32 v118, v118
	v_exp_f32_e32 v116, v116
	v_exp_f32_e32 v117, v117
	v_exp_f32_e32 v119, v119
	v_exp_f32_e32 v106, v106
	v_exp_f32_e32 v104, v104
	v_exp_f32_e32 v105, v105
	v_exp_f32_e32 v107, v107
	v_pk_add_f32 v[116:117], v[116:117], 1.0 op_sel_hi:[1,0]
	v_pk_add_f32 v[118:119], v[118:119], 1.0 op_sel_hi:[1,0]
	v_pk_add_f32 v[104:105], v[104:105], 1.0 op_sel_hi:[1,0]
	v_pk_add_f32 v[106:107], v[106:107], 1.0 op_sel_hi:[1,0]
	v_rcp_f32_e32 v118, v118
	v_rcp_f32_e32 v119, v119
	v_rcp_f32_e32 v116, v116
	v_rcp_f32_e32 v117, v117
	v_rcp_f32_e32 v106, v106
	v_rcp_f32_e32 v104, v104
	v_rcp_f32_e32 v105, v105
	v_rcp_f32_e32 v107, v107
	s_mov_b64 s[4:5], exec
	v_pk_mul_f32 v[74:75], v[10:11], v[186:187] op_sel_hi:[1,0]
	v_pk_mul_f32 v[120:121], v[8:9], v[186:187]
	v_pk_mul_f32 v[72:73], v[6:7], v[186:187] op_sel_hi:[1,0]
	v_pk_mul_f32 v[124:125], v[4:5], v[186:187]
	v_pk_mul_f32 v[102:103], v[102:103], v[116:117]
	v_pk_mul_f32 v[100:101], v[100:101], v[118:119]
	v_pk_mul_f32 v[70:71], v[70:71], v[104:105]
	v_pk_mul_f32 v[68:69], v[68:69], v[106:107]
	v_pk_mul_f32 v[102:103], v[72:73], v[102:103]
	v_pk_mul_f32 v[100:101], v[124:125], v[100:101]
	v_pk_mul_f32 v[70:71], v[74:75], v[70:71]
	v_pk_mul_f32 v[68:69], v[120:121], v[68:69]
	s_nop 0
	v_cvt_pk_bf16_f32 v72, v68, v69
	v_cvt_pk_bf16_f32 v73, v70, v71
	v_cvt_pk_bf16_f32 v74, v100, v101
	v_cvt_pk_bf16_f32 v75, v102, v103

.LBB0_185:
	v_mov_b32_dpp v68, v110 row_shr:1 row_mask:0xf bank_mask:0xf bound_ctrl:1
	v_mov_b32_dpp v72, v114 row_shr:1 row_mask:0xf bank_mask:0xf bound_ctrl:1
	v_mov_b32_dpp v100, v80 row_shr:1 row_mask:0xf bank_mask:0xf bound_ctrl:1
	v_mov_b32_dpp v104, v76 row_shr:1 row_mask:0xf bank_mask:0xf bound_ctrl:1
	v_mov_b32_dpp v69, v111 row_shr:1 row_mask:0xf bank_mask:0xf bound_ctrl:1
	v_mov_b32_dpp v73, v115 row_shr:1 row_mask:0xf bank_mask:0xf bound_ctrl:1
	v_mov_b32_dpp v101, v81 row_shr:1 row_mask:0xf bank_mask:0xf bound_ctrl:1
	v_mov_b32_dpp v105, v77 row_shr:1 row_mask:0xf bank_mask:0xf bound_ctrl:1
	v_mov_b32_dpp v70, v108 row_shr:1 row_mask:0xf bank_mask:0xf bound_ctrl:1
	v_mov_b32_dpp v74, v112 row_shr:1 row_mask:0xf bank_mask:0xf bound_ctrl:1
	v_mov_b32_dpp v102, v82 row_shr:1 row_mask:0xf bank_mask:0xf bound_ctrl:1
	v_mov_b32_dpp v106, v78 row_shr:1 row_mask:0xf bank_mask:0xf bound_ctrl:1
	v_mov_b32_dpp v71, v109 row_shr:1 row_mask:0xf bank_mask:0xf bound_ctrl:1
	v_mov_b32_dpp v75, v113 row_shr:1 row_mask:0xf bank_mask:0xf bound_ctrl:1
	v_mov_b32_dpp v103, v83 row_shr:1 row_mask:0xf bank_mask:0xf bound_ctrl:1
	v_mov_b32_dpp v107, v79 row_shr:1 row_mask:0xf bank_mask:0xf bound_ctrl:1
	s_and_saveexec_b64 s[0:1], s[38:39]
	s_cbranch_execz .LBB0_187
	v_pk_mul_f32 v[34:35], v[34:35], v[192:193] op_sel_hi:[1,0]
	v_pk_mul_f32 v[30:31], v[30:31], v[192:193] op_sel_hi:[1,0]
	v_pk_mul_f32 v[116:117], v[28:29], v[192:193]
	s_waitcnt lgkmcnt(0)
	v_pk_fma_f32 v[28:29], v[58:59], v[106:107], v[66:67]
	v_pk_fma_f32 v[104:105], v[56:57], v[104:105], v[64:65]
	v_pk_fma_f32 v[28:29], v[62:63], v[74:75], v[28:29]
	v_pk_fma_f32 v[104:105], v[60:61], v[72:73], v[104:105]
	v_pk_fma_f32 v[106:107], v[94:95], v[54:55], v[28:29]
	v_pk_fma_f32 v[104:105], v[92:93], v[52:53], v[104:105]
	s_mov_b32 s4, 0xc0135761
	v_pk_mul_f32 v[118:119], v[106:107], v[106:107]
	v_pk_mul_f32 v[120:121], v[104:105], v[104:105]
	v_mov_b64_e32 v[28:29], s[4:5]
	s_mov_b32 s6, 0x3dd2d3e2
	v_pk_fma_f32 v[118:119], v[118:119], s[6:7], v[28:29] op_sel_hi:[1,0,0] neg_lo:[1,0,0] neg_hi:[1,0,0]
	v_pk_fma_f32 v[120:121], v[120:121], s[6:7], v[28:29] op_sel_hi:[1,0,0] neg_lo:[1,0,0] neg_hi:[1,0,0]
	v_pk_mul_f32 v[118:119], v[106:107], v[118:119]
	v_pk_mul_f32 v[120:121], v[104:105], v[120:121]
	v_exp_f32_e32 v118, v118
	v_exp_f32_e32 v120, v120
	v_exp_f32_e32 v121, v121
	v_exp_f32_e32 v119, v119
	v_pk_fma_f32 v[102:103], v[42:43], v[102:103], v[50:51]
	v_pk_fma_f32 v[100:101], v[40:41], v[100:101], v[48:49]
	v_pk_add_f32 v[120:121], v[120:121], 1.0 op_sel_hi:[1,0]
	v_pk_add_f32 v[118:119], v[118:119], 1.0 op_sel_hi:[1,0]
	v_rcp_f32_e32 v120, v120
	v_rcp_f32_e32 v121, v121
	v_rcp_f32_e32 v118, v118
	v_rcp_f32_e32 v119, v119
	v_pk_fma_f32 v[102:103], v[46:47], v[70:71], v[102:103]
	v_pk_fma_f32 v[100:101], v[44:45], v[68:69], v[100:101]
	v_pk_mul_f32 v[32:33], v[32:33], v[192:193]
	v_pk_mul_f32 v[106:107], v[106:107], v[118:119]
	v_pk_mul_f32 v[104:105], v[104:105], v[120:121]
	v_pk_fma_f32 v[102:103], v[98:99], v[38:39], v[102:103]
	v_pk_fma_f32 v[100:101], v[96:97], v[36:37], v[100:101]
	v_pk_mul_f32 v[34:35], v[34:35], v[106:107]
	v_pk_mul_f32 v[32:33], v[32:33], v[104:105]
	v_pk_mul_f32 v[104:105], v[102:103], v[102:103]
	v_pk_mul_f32 v[106:107], v[100:101], v[100:101]
	v_pk_fma_f32 v[104:105], v[104:105], s[6:7], v[28:29] op_sel_hi:[1,0,0] neg_lo:[1,0,0] neg_hi:[1,0,0]
	v_pk_fma_f32 v[106:107], v[106:107], s[6:7], v[28:29] op_sel_hi:[1,0,0] neg_lo:[1,0,0] neg_hi:[1,0,0]
	v_pk_mul_f32 v[104:105], v[102:103], v[104:105]
	v_pk_mul_f32 v[106:107], v[100:101], v[106:107]
	v_exp_f32_e32 v104, v104
	v_exp_f32_e32 v106, v106
	v_exp_f32_e32 v107, v107
	v_exp_f32_e32 v105, v105
	v_add_u32_e32 v2, s8, v235
	v_pk_mul_f32 v[24:25], v[24:25], v[190:191]
	v_pk_add_f32 v[106:107], v[106:107], 1.0 op_sel_hi:[1,0]
	v_pk_add_f32 v[104:105], v[104:105], 1.0 op_sel_hi:[1,0]
	v_rcp_f32_e32 v106, v106
	v_rcp_f32_e32 v107, v107
	v_rcp_f32_e32 v104, v104
	v_rcp_f32_e32 v105, v105
	v_pk_mul_f32 v[20:21], v[20:21], v[190:191]
	v_pk_mul_f32 v[100:101], v[100:101], v[106:107]
	v_pk_mul_f32 v[102:103], v[102:103], v[104:105]
	s_nop 0
	v_pk_mul_f32 v[102:103], v[30:31], v[102:103]
	v_pk_mul_f32 v[30:31], v[116:117], v[100:101]
	s_nop 0
	v_cvt_pk_bf16_f32 v30, v30, v31
	v_cvt_pk_bf16_f32 v31, v102, v103
	v_cvt_pk_bf16_f32 v32, v32, v33
	v_cvt_pk_bf16_f32 v33, v34, v35
	v_mad_u32_u24 v100, v2, s33, v185
	global_store_dwordx4 v100, v[30:33], s[96:97]
	v_add_u32_e32 v2, s8, v236
	s_nop 0
	v_pk_mul_f32 v[26:27], v[26:27], v[190:191] op_sel_hi:[1,0]
	v_pk_mul_f32 v[22:23], v[22:23], v[190:191] op_sel_hi:[1,0]
	v_pk_fma_f32 v[30:31], v[58:59], v[74:75], v[66:67]
	v_pk_fma_f32 v[32:33], v[56:57], v[72:73], v[64:65]
	v_pk_fma_f32 v[30:31], v[94:95], v[62:63], v[30:31]
	v_pk_fma_f32 v[32:33], v[92:93], v[60:61], v[32:33]
	v_pk_fma_f32 v[30:31], v[86:87], v[54:55], v[30:31]
	v_pk_fma_f32 v[32:33], v[84:85], v[52:53], v[32:33]
	v_pk_mul_f32 v[72:73], v[30:31], v[30:31]
	v_pk_mul_f32 v[74:75], v[32:33], v[32:33]
	v_pk_fma_f32 v[72:73], v[72:73], s[6:7], v[28:29] op_sel_hi:[1,0,0] neg_lo:[1,0,0] neg_hi:[1,0,0]
	v_pk_fma_f32 v[74:75], v[74:75], s[6:7], v[28:29] op_sel_hi:[1,0,0] neg_lo:[1,0,0] neg_hi:[1,0,0]
	v_pk_mul_f32 v[72:73], v[30:31], v[72:73]
	v_pk_mul_f32 v[74:75], v[32:33], v[74:75]
	v_exp_f32_e32 v72, v72
	v_exp_f32_e32 v74, v74
	v_exp_f32_e32 v75, v75
	v_exp_f32_e32 v73, v73
	v_pk_add_f32 v[74:75], v[74:75], 1.0 op_sel_hi:[1,0]
	v_pk_add_f32 v[72:73], v[72:73], 1.0 op_sel_hi:[1,0]
	v_rcp_f32_e32 v74, v74
	v_rcp_f32_e32 v75, v75
	v_rcp_f32_e32 v72, v72
	v_rcp_f32_e32 v73, v73
	v_pk_mul_f32 v[32:33], v[32:33], v[74:75]
	s_nop 0
	v_pk_mul_f32 v[24:25], v[24:25], v[32:33]
	v_pk_mul_f32 v[30:31], v[30:31], v[72:73]
	v_pk_fma_f32 v[32:33], v[40:41], v[68:69], v[48:49]
	v_pk_mul_f32 v[26:27], v[26:27], v[30:31]
	v_pk_fma_f32 v[30:31], v[42:43], v[70:71], v[50:51]
	v_pk_fma_f32 v[32:33], v[96:97], v[44:45], v[32:33]
	v_pk_fma_f32 v[30:31], v[98:99], v[46:47], v[30:31]
	v_pk_fma_f32 v[32:33], v[88:89], v[36:37], v[32:33]
	v_pk_fma_f32 v[30:31], v[90:91], v[38:39], v[30:31]
	v_pk_mul_f32 v[70:71], v[32:33], v[32:33]
	v_pk_mul_f32 v[68:69], v[30:31], v[30:31]
	v_pk_fma_f32 v[70:71], v[70:71], s[6:7], v[28:29] op_sel_hi:[1,0,0] neg_lo:[1,0,0] neg_hi:[1,0,0]
	v_pk_fma_f32 v[28:29], v[68:69], s[6:7], v[28:29] op_sel_hi:[1,0,0] neg_lo:[1,0,0] neg_hi:[1,0,0]
	v_pk_mul_f32 v[68:69], v[32:33], v[70:71]
	v_pk_mul_f32 v[28:29], v[30:31], v[28:29]
	v_exp_f32_e32 v68, v68
	v_exp_f32_e32 v69, v69
	v_exp_f32_e32 v28, v28
	v_exp_f32_e32 v29, v29
	v_pk_add_f32 v[68:69], v[68:69], 1.0 op_sel_hi:[1,0]
	s_nop 0
	v_rcp_f32_e32 v68, v68
	v_pk_add_f32 v[28:29], v[28:29], 1.0 op_sel_hi:[1,0]
	v_rcp_f32_e32 v69, v69
	v_rcp_f32_e32 v28, v28
	v_rcp_f32_e32 v29, v29
	s_nop 0
	v_pk_mul_f32 v[28:29], v[30:31], v[28:29]
	v_pk_mul_f32 v[30:31], v[32:33], v[68:69]
	v_pk_mul_f32 v[22:23], v[22:23], v[28:29]
	v_pk_mul_f32 v[20:21], v[20:21], v[30:31]
	s_nop 0
	v_cvt_pk_bf16_f32 v20, v20, v21
	v_cvt_pk_bf16_f32 v21, v22, v23
	v_cvt_pk_bf16_f32 v22, v24, v25
	v_mad_u32_u24 v24, v2, s33, v185
	v_cvt_pk_bf16_f32 v23, v26, v27
	global_store_dwordx4 v24, v[20:23], s[96:97]
.LBB0_187:
	s_or_b64 exec, exec, s[0:1]
	s_nop 0
	v_pk_mul_f32 v[18:19], v[18:19], v[188:189] op_sel_hi:[1,0]
	v_pk_mul_f32 v[14:15], v[14:15], v[188:189] op_sel_hi:[1,0]
	v_pk_mul_f32 v[20:21], v[12:13], v[188:189]
	s_waitcnt lgkmcnt(0)
	v_pk_fma_f32 v[12:13], v[94:95], v[58:59], v[66:67]
	v_pk_fma_f32 v[22:23], v[92:93], v[56:57], v[64:65]
	v_pk_fma_f32 v[12:13], v[86:87], v[62:63], v[12:13]
	v_pk_fma_f32 v[22:23], v[84:85], v[60:61], v[22:23]
	v_pk_fma_f32 v[24:25], v[78:79], v[54:55], v[12:13]
	v_pk_fma_f32 v[22:23], v[76:77], v[52:53], v[22:23]
	s_mov_b32 s0, 0xc0135761
	v_pk_mul_f32 v[26:27], v[24:25], v[24:25]
	v_pk_mul_f32 v[28:29], v[22:23], v[22:23]
	v_mov_b64_e32 v[12:13], s[0:1]
	s_mov_b32 s4, 0x3dd2d3e2
	v_pk_fma_f32 v[26:27], v[26:27], s[4:5], v[12:13] op_sel_hi:[1,0,0] neg_lo:[1,0,0] neg_hi:[1,0,0]
	v_pk_fma_f32 v[28:29], v[28:29], s[4:5], v[12:13] op_sel_hi:[1,0,0] neg_lo:[1,0,0] neg_hi:[1,0,0]
	v_pk_mul_f32 v[26:27], v[24:25], v[26:27]
	v_pk_mul_f32 v[28:29], v[22:23], v[28:29]
	v_exp_f32_e32 v26, v26
	v_exp_f32_e32 v28, v28
	v_exp_f32_e32 v29, v29
	v_exp_f32_e32 v27, v27
	v_pk_mul_f32 v[16:17], v[16:17], v[188:189]
	v_add_u32_e32 v2, s8, v223
	v_pk_add_f32 v[28:29], v[28:29], 1.0 op_sel_hi:[1,0]
	v_pk_add_f32 v[26:27], v[26:27], 1.0 op_sel_hi:[1,0]
	v_rcp_f32_e32 v28, v28
	v_rcp_f32_e32 v29, v29
	v_rcp_f32_e32 v26, v26
	v_rcp_f32_e32 v27, v27
	v_pk_mul_f32 v[4:5], v[4:5], v[186:187]
	v_pk_mul_f32 v[22:23], v[22:23], v[28:29]
	v_pk_mul_f32 v[8:9], v[8:9], v[186:187]
	v_pk_mul_f32 v[24:25], v[24:25], v[26:27]
	v_pk_mul_f32 v[20:21], v[20:21], v[22:23]
	v_pk_mul_f32 v[24:25], v[14:15], v[24:25]
	v_pk_fma_f32 v[14:15], v[98:99], v[42:43], v[50:51]
	v_pk_fma_f32 v[22:23], v[96:97], v[40:41], v[48:49]
	v_pk_fma_f32 v[14:15], v[90:91], v[46:47], v[14:15]
	v_pk_fma_f32 v[22:23], v[88:89], v[44:45], v[22:23]
	v_pk_fma_f32 v[14:15], v[82:83], v[38:39], v[14:15]
	v_pk_fma_f32 v[22:23], v[80:81], v[36:37], v[22:23]
	v_pk_mul_f32 v[26:27], v[14:15], v[14:15]
	v_pk_mul_f32 v[28:29], v[22:23], v[22:23]
	v_pk_fma_f32 v[26:27], v[26:27], s[4:5], v[12:13] op_sel_hi:[1,0,0] neg_lo:[1,0,0] neg_hi:[1,0,0]
	v_pk_fma_f32 v[28:29], v[28:29], s[4:5], v[12:13] op_sel_hi:[1,0,0] neg_lo:[1,0,0] neg_hi:[1,0,0]
	v_pk_mul_f32 v[26:27], v[14:15], v[26:27]
	v_pk_mul_f32 v[28:29], v[22:23], v[28:29]
	v_exp_f32_e32 v26, v26
	v_exp_f32_e32 v28, v28
	v_exp_f32_e32 v29, v29
	v_exp_f32_e32 v27, v27
	v_pk_add_f32 v[28:29], v[28:29], 1.0 op_sel_hi:[1,0]
	v_pk_add_f32 v[26:27], v[26:27], 1.0 op_sel_hi:[1,0]
	v_rcp_f32_e32 v28, v28
	v_rcp_f32_e32 v29, v29
	v_rcp_f32_e32 v26, v26
	v_rcp_f32_e32 v27, v27
	v_pk_mul_f32 v[22:23], v[22:23], v[28:29]
	v_pk_mul_f32 v[14:15], v[14:15], v[26:27]
	s_nop 0
	v_pk_mul_f32 v[18:19], v[18:19], v[14:15]
	v_pk_mul_f32 v[14:15], v[16:17], v[22:23]
	s_nop 0
	v_cvt_pk_bf16_f32 v14, v14, v15
	v_cvt_pk_bf16_f32 v15, v18, v19
	v_mad_u32_u24 v18, v2, s33, v185
	v_cvt_pk_bf16_f32 v16, v20, v21
	v_cvt_pk_bf16_f32 v17, v24, v25
	global_store_dwordx4 v18, v[14:17], s[96:97]
	v_add_u32_e32 v2, s8, v233
	s_nop 0
	v_pk_mul_f32 v[10:11], v[10:11], v[186:187] op_sel_hi:[1,0]
	v_pk_mul_f32 v[6:7], v[6:7], v[186:187] op_sel_hi:[1,0]
	v_pk_fma_f32 v[14:15], v[86:87], v[58:59], v[66:67]
	v_pk_fma_f32 v[16:17], v[84:85], v[56:57], v[64:65]
	v_pk_fma_f32 v[14:15], v[78:79], v[62:63], v[14:15]
	v_pk_fma_f32 v[16:17], v[76:77], v[60:61], v[16:17]
	v_pk_fma_f32 v[14:15], v[112:113], v[54:55], v[14:15]
	v_pk_fma_f32 v[16:17], v[114:115], v[52:53], v[16:17]
	v_pk_mul_f32 v[18:19], v[14:15], v[14:15]
	v_pk_mul_f32 v[20:21], v[16:17], v[16:17]
	v_pk_fma_f32 v[18:19], v[18:19], s[4:5], v[12:13] op_sel_hi:[1,0,0] neg_lo:[1,0,0] neg_hi:[1,0,0]
	v_pk_fma_f32 v[20:21], v[20:21], s[4:5], v[12:13] op_sel_hi:[1,0,0] neg_lo:[1,0,0] neg_hi:[1,0,0]
	v_pk_mul_f32 v[18:19], v[14:15], v[18:19]
	v_pk_mul_f32 v[20:21], v[16:17], v[20:21]
	v_exp_f32_e32 v18, v18
	v_exp_f32_e32 v20, v20
	v_exp_f32_e32 v21, v21
	v_exp_f32_e32 v19, v19
	v_pk_add_f32 v[20:21], v[20:21], 1.0 op_sel_hi:[1,0]
	v_pk_add_f32 v[18:19], v[18:19], 1.0 op_sel_hi:[1,0]
	v_rcp_f32_e32 v20, v20
	v_rcp_f32_e32 v21, v21
	v_rcp_f32_e32 v18, v18
	v_rcp_f32_e32 v19, v19
	v_pk_mul_f32 v[16:17], v[16:17], v[20:21]
	s_nop 0
	v_pk_mul_f32 v[4:5], v[4:5], v[16:17]
	v_pk_mul_f32 v[14:15], v[14:15], v[18:19]
	v_pk_fma_f32 v[16:17], v[40:41], v[88:89], v[48:49]
	v_pk_mul_f32 v[6:7], v[6:7], v[14:15]
	v_pk_fma_f32 v[14:15], v[42:43], v[90:91], v[50:51]
	v_pk_fma_f32 v[16:17], v[80:81], v[44:45], v[16:17]
	v_pk_fma_f32 v[14:15], v[82:83], v[46:47], v[14:15]
	v_pk_fma_f32 v[16:17], v[110:111], v[36:37], v[16:17]
	v_pk_fma_f32 v[14:15], v[108:109], v[38:39], v[14:15]
	v_pk_mul_f32 v[20:21], v[16:17], v[16:17]
	v_pk_mul_f32 v[18:19], v[14:15], v[14:15]
	s_nop 0
	v_pk_fma_f32 v[18:19], v[18:19], s[4:5], v[12:13] op_sel_hi:[1,0,0] neg_lo:[1,0,0] neg_hi:[1,0,0]
	v_pk_fma_f32 v[12:13], v[20:21], s[4:5], v[12:13] op_sel_hi:[1,0,0] neg_lo:[1,0,0] neg_hi:[1,0,0]
	v_pk_mul_f32 v[18:19], v[14:15], v[18:19]
	v_pk_mul_f32 v[12:13], v[16:17], v[12:13]
	v_exp_f32_e32 v18, v18
	v_exp_f32_e32 v12, v12
	v_exp_f32_e32 v13, v13
	v_exp_f32_e32 v19, v19
	s_mov_b64 s[4:5], -1
	v_pk_add_f32 v[12:13], v[12:13], 1.0 op_sel_hi:[1,0]
	v_pk_add_f32 v[18:19], v[18:19], 1.0 op_sel_hi:[1,0]
	v_rcp_f32_e32 v12, v12
	v_rcp_f32_e32 v13, v13
	v_rcp_f32_e32 v18, v18
	v_rcp_f32_e32 v19, v19
	v_pk_mul_f32 v[12:13], v[16:17], v[12:13]
	s_nop 0
	v_pk_mul_f32 v[8:9], v[8:9], v[12:13]
	v_pk_mul_f32 v[14:15], v[14:15], v[18:19]
	v_cvt_pk_bf16_f32 v72, v8, v9
	s_nop 0
	v_pk_mul_f32 v[10:11], v[10:11], v[14:15]
	s_nop 0
	v_cvt_pk_bf16_f32 v73, v10, v11
	v_cvt_pk_bf16_f32 v74, v4, v5
	v_cvt_pk_bf16_f32 v75, v6, v7
	s_and_saveexec_b64 s[0:1], s[4:5]
	s_cbranch_execnz .LBB0_177
